# stack3 + remaining contiguous wave-sum chains (nyq, combine) converted to DPP/permlane butterflies
# baseline (speedup 1.0000x reference)
; __device__ __forceinline__ float shfl_xor_f(float v, int o) {
;     int l; asm volatile("v_mbcnt_lo_u32_b32 %0, -1, 0\n\tv_mbcnt_hi_u32_b32 %0, -1, %0" : "=v"(l));
;     return __builtin_bit_cast(float, __builtin_amdgcn_ds_bpermute((l ^ o) << 2, __builtin_bit_cast(int, v)));
; }
; __device__ __forceinline__ float wave_sum(float v) {
; #pragma unroll
;     for (int o = 1; o < 64; o <<= 1) v += shfl_xor_f(v, o);
;     return v;
; __device__ __forceinline__ void nyq_phase(const bf16* H, const bf16* WfT, float* nyq, int gw, int NGW, int lane) {
;     ...
;         for (int b = 0; b < 4; ++b) { const v4u* hp = (const v4u*)(H + (size_t)(b * SEQ + SEQ / 2) * DM) + lane; float s = 0.f;
; #pragma unroll
;             for (int j = 0; j < 4; ++j) { const v4u hv = hp[64 * j];
; #pragma unroll
;                 for (int e = 0; e < 4; ++e) s += bflo(wv[j][e]) * bflo(hv[e]) + bfhi(wv[j][e]) * bfhi(hv[e]); }
;             s = wave_sum(s); if (lane == 0) nyq[b * 1024 + ch] = s; }
.LBB0_526:
	s_or_b64 exec, exec, s[70:71]
	s_waitcnt vmcnt(12) lgkmcnt(0)
	v_and_b32_e32 v43, 0xffff0000, v52
	v_lshlrev_b32_e32 v7, 16, v52
	v_mul_f32_e32 v43, v20, v43
	v_fmac_f32_e32 v43, v18, v7
	v_and_b32_e32 v44, 0xffff0000, v53
	v_add_f32_e32 v7, 0, v43
	v_lshlrev_b32_e32 v43, 16, v53
	v_mul_f32_e32 v44, v22, v44
	v_fmac_f32_e32 v44, v19, v43
	v_add_f32_e32 v7, v44, v7
	v_and_b32_e32 v44, 0xffff0000, v54
	v_lshlrev_b32_e32 v43, 16, v54
	v_mul_f32_e32 v44, v24, v44
	v_fmac_f32_e32 v44, v21, v43
	v_add_f32_e32 v7, v44, v7
	v_and_b32_e32 v44, 0xffff0000, v55
	v_lshlrev_b32_e32 v43, 16, v55
	v_mul_f32_e32 v44, v25, v44
	v_fmac_f32_e32 v44, v23, v43
	v_add_f32_e32 v7, v44, v7
	s_waitcnt vmcnt(11)
	v_lshlrev_b32_e32 v43, 16, v56
	v_and_b32_e32 v44, 0xffff0000, v56
	v_mul_f32_e32 v44, v28, v44
	v_fmac_f32_e32 v44, v26, v43
	v_add_f32_e32 v7, v44, v7
	v_and_b32_e32 v44, 0xffff0000, v57
	v_lshlrev_b32_e32 v43, 16, v57
	v_mul_f32_e32 v44, v30, v44
	v_fmac_f32_e32 v44, v27, v43
	v_add_f32_e32 v7, v44, v7
	v_and_b32_e32 v44, 0xffff0000, v58
	v_lshlrev_b32_e32 v43, 16, v58
	v_mul_f32_e32 v44, v32, v44
	v_fmac_f32_e32 v44, v29, v43
	v_add_f32_e32 v7, v44, v7
	v_and_b32_e32 v44, 0xffff0000, v59
	v_lshlrev_b32_e32 v43, 16, v59
	v_mul_f32_e32 v44, v33, v44
	v_fmac_f32_e32 v44, v31, v43
	v_add_f32_e32 v7, v44, v7
	s_waitcnt vmcnt(10)
	v_lshlrev_b32_e32 v43, 16, v60
	v_and_b32_e32 v44, 0xffff0000, v60
	v_mul_f32_e32 v44, v36, v44
	v_fmac_f32_e32 v44, v34, v43
	v_add_f32_e32 v7, v44, v7
	v_and_b32_e32 v44, 0xffff0000, v61
	v_lshlrev_b32_e32 v43, 16, v61
	v_mul_f32_e32 v44, v38, v44
	v_fmac_f32_e32 v44, v35, v43
	v_add_f32_e32 v7, v44, v7
	v_and_b32_e32 v44, 0xffff0000, v62
	v_lshlrev_b32_e32 v43, 16, v62
	v_mul_f32_e32 v44, v40, v44
	v_fmac_f32_e32 v44, v37, v43
	v_add_f32_e32 v7, v44, v7
	v_and_b32_e32 v44, 0xffff0000, v63
	v_lshlrev_b32_e32 v43, 16, v63
	v_mul_f32_e32 v44, v41, v44
	v_fmac_f32_e32 v44, v39, v43
	v_add_f32_e32 v7, v44, v7
	s_waitcnt vmcnt(9)
	v_lshlrev_b32_e32 v43, 16, v64
	v_and_b32_e32 v44, 0xffff0000, v64
	v_mul_f32_e32 v44, v0, v44
	v_fmac_f32_e32 v44, v42, v43
	v_add_f32_e32 v7, v44, v7
	v_and_b32_e32 v44, 0xffff0000, v65
	v_lshlrev_b32_e32 v43, 16, v65
	v_mul_f32_e32 v44, v1, v44
	v_fmac_f32_e32 v44, v4, v43
	v_add_f32_e32 v7, v44, v7
	v_and_b32_e32 v44, 0xffff0000, v66
	v_lshlrev_b32_e32 v43, 16, v66
	v_mul_f32_e32 v44, v2, v44
	v_fmac_f32_e32 v44, v5, v43
	v_add_f32_e32 v7, v44, v7
	v_and_b32_e32 v44, 0xffff0000, v67
	v_lshlrev_b32_e32 v43, 16, v67
	v_mul_f32_e32 v44, v3, v44
	v_fmac_f32_e32 v44, v6, v43
	v_add_f32_e32 v7, v44, v7
	s_waitcnt lgkmcnt(0)
	s_nop 1
	v_add_f32_dpp v7, v7, v7 quad_perm:[1,0,3,2] row_mask:0xf bank_mask:0xf
	s_waitcnt lgkmcnt(0)
	s_nop 1
	v_add_f32_dpp v7, v7, v7 quad_perm:[2,3,0,1] row_mask:0xf bank_mask:0xf
	s_waitcnt lgkmcnt(0)
	s_nop 1
	v_add_f32_dpp v7, v7, v7 row_half_mirror row_mask:0xf bank_mask:0xf
	s_waitcnt lgkmcnt(0)
	s_nop 1
	v_add_f32_dpp v7, v7, v7 row_mirror row_mask:0xf bank_mask:0xf
	s_waitcnt lgkmcnt(0)
	v_mov_b32_e32 v43, v7
	s_nop 1
	v_permlane16_swap_b32_e32 v43, v7
	s_nop 1
	v_add_f32_e32 v7, v7, v43
	v_mov_b32_e32 v43, v7
	s_nop 1
	v_permlane32_swap_b32_e32 v43, v7
	s_nop 1
	s_and_saveexec_b64 s[70:71], vcc
	s_cbranch_execz .LBB0_528
	s_add_u32 s2, s0, s60
	s_waitcnt lgkmcnt(0)
	v_add_f32_e32 v7, v7, v43
	s_addc_u32 s3, s1, 0
	v_mov_b32_e32 v43, 0x781000
	global_store_dword v43, v7, s[2:3]
; __device__ __forceinline__ float shfl_xor_f(float v, int o) {
;     int l; asm volatile("v_mbcnt_lo_u32_b32 %0, -1, 0\n\tv_mbcnt_hi_u32_b32 %0, -1, %0" : "=v"(l));
;     return __builtin_bit_cast(float, __builtin_amdgcn_ds_bpermute((l ^ o) << 2, __builtin_bit_cast(int, v)));
; }
; __device__ __forceinline__ float wave_sum(float v) {
; #pragma unroll
;     for (int o = 1; o < 64; o <<= 1) v += shfl_xor_f(v, o);
;     return v;
; __device__ __forceinline__ void nyq_phase(const bf16* H, const bf16* WfT, float* nyq, int gw, int NGW, int lane) {
;     ...
;         for (int b = 0; b < 4; ++b) { const v4u* hp = (const v4u*)(H + (size_t)(b * SEQ + SEQ / 2) * DM) + lane; float s = 0.f;
; #pragma unroll
;             for (int j = 0; j < 4; ++j) { const v4u hv = hp[64 * j];
; #pragma unroll
;                 for (int e = 0; e < 4; ++e) s += bflo(wv[j][e]) * bflo(hv[e]) + bfhi(wv[j][e]) * bfhi(hv[e]); }
;             s = wave_sum(s); if (lane == 0) nyq[b * 1024 + ch] = s; }
.LBB0_528:
	s_or_b64 exec, exec, s[70:71]
	s_waitcnt vmcnt(9) lgkmcnt(0)
	v_and_b32_e32 v43, 0xffff0000, v68
	v_lshlrev_b32_e32 v7, 16, v68
	v_mul_f32_e32 v43, v20, v43
	v_fmac_f32_e32 v43, v18, v7
	v_and_b32_e32 v44, 0xffff0000, v69
	v_add_f32_e32 v7, 0, v43
	v_lshlrev_b32_e32 v43, 16, v69
	v_mul_f32_e32 v44, v22, v44
	v_fmac_f32_e32 v44, v19, v43
	v_add_f32_e32 v7, v44, v7
	v_and_b32_e32 v44, 0xffff0000, v70
	v_lshlrev_b32_e32 v43, 16, v70
	v_mul_f32_e32 v44, v24, v44
	v_fmac_f32_e32 v44, v21, v43
	v_add_f32_e32 v7, v44, v7
	v_and_b32_e32 v44, 0xffff0000, v71
	v_lshlrev_b32_e32 v43, 16, v71
	v_mul_f32_e32 v44, v25, v44
	v_fmac_f32_e32 v44, v23, v43
	v_add_f32_e32 v7, v44, v7
	s_waitcnt vmcnt(8)
	v_lshlrev_b32_e32 v43, 16, v72
	v_and_b32_e32 v44, 0xffff0000, v72
	v_mul_f32_e32 v44, v28, v44
	v_fmac_f32_e32 v44, v26, v43
	v_add_f32_e32 v7, v44, v7
	v_and_b32_e32 v44, 0xffff0000, v73
	v_lshlrev_b32_e32 v43, 16, v73
	v_mul_f32_e32 v44, v30, v44
	v_fmac_f32_e32 v44, v27, v43
	v_add_f32_e32 v7, v44, v7
	v_and_b32_e32 v44, 0xffff0000, v74
	v_lshlrev_b32_e32 v43, 16, v74
	v_mul_f32_e32 v44, v32, v44
	v_fmac_f32_e32 v44, v29, v43
	v_add_f32_e32 v7, v44, v7
	v_and_b32_e32 v44, 0xffff0000, v75
	v_lshlrev_b32_e32 v43, 16, v75
	v_mul_f32_e32 v44, v33, v44
	v_fmac_f32_e32 v44, v31, v43
	v_add_f32_e32 v7, v44, v7
	s_waitcnt vmcnt(7)
	v_lshlrev_b32_e32 v43, 16, v76
	v_and_b32_e32 v44, 0xffff0000, v76
	v_mul_f32_e32 v44, v36, v44
	v_fmac_f32_e32 v44, v34, v43
	v_add_f32_e32 v7, v44, v7
	v_and_b32_e32 v44, 0xffff0000, v77
	v_lshlrev_b32_e32 v43, 16, v77
	v_mul_f32_e32 v44, v38, v44
	v_fmac_f32_e32 v44, v35, v43
	v_add_f32_e32 v7, v44, v7
	v_and_b32_e32 v44, 0xffff0000, v78
	v_lshlrev_b32_e32 v43, 16, v78
	v_mul_f32_e32 v44, v40, v44
	v_fmac_f32_e32 v44, v37, v43
	v_add_f32_e32 v7, v44, v7
	v_and_b32_e32 v44, 0xffff0000, v79
	v_lshlrev_b32_e32 v43, 16, v79
	v_mul_f32_e32 v44, v41, v44
	v_fmac_f32_e32 v44, v39, v43
	v_add_f32_e32 v7, v44, v7
	s_waitcnt vmcnt(6)
	v_lshlrev_b32_e32 v43, 16, v80
	v_and_b32_e32 v44, 0xffff0000, v80
	v_mul_f32_e32 v44, v0, v44
	v_fmac_f32_e32 v44, v42, v43
	v_add_f32_e32 v7, v44, v7
	v_and_b32_e32 v44, 0xffff0000, v81
	v_lshlrev_b32_e32 v43, 16, v81
	v_mul_f32_e32 v44, v1, v44
	v_fmac_f32_e32 v44, v4, v43
	v_add_f32_e32 v7, v44, v7
	v_and_b32_e32 v44, 0xffff0000, v82
	v_lshlrev_b32_e32 v43, 16, v82
	v_mul_f32_e32 v44, v2, v44
	v_fmac_f32_e32 v44, v5, v43
	v_add_f32_e32 v7, v44, v7
	v_and_b32_e32 v44, 0xffff0000, v83
	v_lshlrev_b32_e32 v43, 16, v83
	v_mul_f32_e32 v44, v3, v44
	v_fmac_f32_e32 v44, v6, v43
	v_add_f32_e32 v7, v44, v7
	s_waitcnt lgkmcnt(0)
	s_nop 1
	v_add_f32_dpp v7, v7, v7 quad_perm:[1,0,3,2] row_mask:0xf bank_mask:0xf
	s_waitcnt lgkmcnt(0)
	s_nop 1
	v_add_f32_dpp v7, v7, v7 quad_perm:[2,3,0,1] row_mask:0xf bank_mask:0xf
	s_waitcnt lgkmcnt(0)
	s_nop 1
	v_add_f32_dpp v7, v7, v7 row_half_mirror row_mask:0xf bank_mask:0xf
	s_waitcnt lgkmcnt(0)
	s_nop 1
	v_add_f32_dpp v7, v7, v7 row_mirror row_mask:0xf bank_mask:0xf
	s_waitcnt lgkmcnt(0)
	v_mov_b32_e32 v43, v7
	s_nop 1
	v_permlane16_swap_b32_e32 v43, v7
	s_nop 1
	v_add_f32_e32 v7, v7, v43
	v_mov_b32_e32 v43, v7
	s_nop 1
	v_permlane32_swap_b32_e32 v43, v7
	s_nop 1
	s_and_saveexec_b64 s[70:71], vcc
	s_cbranch_execz .LBB0_530
	s_add_u32 s2, s0, s60
	s_waitcnt lgkmcnt(0)
	v_add_f32_e32 v7, v7, v43
	s_addc_u32 s3, s1, 0
	v_mov_b32_e32 v43, 0x782000
	global_store_dword v43, v7, s[2:3]
.LBB0_530:
	s_or_b64 exec, exec, s[70:71]
	s_waitcnt vmcnt(6) lgkmcnt(0)
	v_and_b32_e32 v43, 0xffff0000, v84
	v_lshlrev_b32_e32 v7, 16, v84
	v_mul_f32_e32 v20, v20, v43
	v_fmac_f32_e32 v20, v18, v7
	v_add_f32_e32 v7, 0, v20
	v_and_b32_e32 v20, 0xffff0000, v85
	v_lshlrev_b32_e32 v18, 16, v85
	v_mul_f32_e32 v20, v22, v20
	v_fmac_f32_e32 v20, v19, v18
	v_and_b32_e32 v19, 0xffff0000, v86
	v_lshlrev_b32_e32 v18, 16, v86
	v_mul_f32_e32 v19, v24, v19
	v_add_f32_e32 v7, v20, v7
	v_fmac_f32_e32 v19, v21, v18
	v_add_f32_e32 v7, v19, v7
	v_and_b32_e32 v19, 0xffff0000, v87
	v_lshlrev_b32_e32 v18, 16, v87
	v_mul_f32_e32 v19, v25, v19
	v_fmac_f32_e32 v19, v23, v18
	v_add_f32_e32 v7, v19, v7
	s_waitcnt vmcnt(5)
	v_lshlrev_b32_e32 v22, 16, v88
	v_and_b32_e32 v18, 0xffff0000, v88
	v_mul_f32_e32 v18, v28, v18
	v_fmac_f32_e32 v18, v26, v22
	v_add_f32_e32 v7, v18, v7
	v_lshlrev_b32_e32 v18, 16, v89
	v_and_b32_e32 v19, 0xffff0000, v89
	v_mul_f32_e32 v19, v30, v19
	v_fmac_f32_e32 v19, v27, v18
	v_add_f32_e32 v7, v19, v7
	v_and_b32_e32 v19, 0xffff0000, v90
	v_lshlrev_b32_e32 v18, 16, v90
	v_mul_f32_e32 v19, v32, v19
	v_fmac_f32_e32 v19, v29, v18
	v_add_f32_e32 v7, v19, v7
	v_and_b32_e32 v19, 0xffff0000, v91
	v_lshlrev_b32_e32 v18, 16, v91
	v_mul_f32_e32 v19, v33, v19
	v_fmac_f32_e32 v19, v31, v18
	v_add_f32_e32 v7, v19, v7
	s_waitcnt vmcnt(4)
	v_lshlrev_b32_e32 v22, 16, v92
	v_and_b32_e32 v18, 0xffff0000, v92
	v_mul_f32_e32 v18, v36, v18
	v_fmac_f32_e32 v18, v34, v22
	v_add_f32_e32 v7, v18, v7
	v_lshlrev_b32_e32 v18, 16, v93
	v_and_b32_e32 v19, 0xffff0000, v93
	v_mul_f32_e32 v19, v38, v19
	v_fmac_f32_e32 v19, v35, v18
	v_add_f32_e32 v7, v19, v7
	v_and_b32_e32 v19, 0xffff0000, v94
	v_lshlrev_b32_e32 v18, 16, v94
	v_mul_f32_e32 v19, v40, v19
	v_fmac_f32_e32 v19, v37, v18
	v_add_f32_e32 v7, v19, v7
	v_and_b32_e32 v19, 0xffff0000, v95
	v_lshlrev_b32_e32 v18, 16, v95
	v_mul_f32_e32 v19, v41, v19
	v_fmac_f32_e32 v19, v39, v18
	v_add_f32_e32 v7, v19, v7
	s_waitcnt vmcnt(3)
	v_lshlrev_b32_e32 v22, 16, v96
	v_and_b32_e32 v18, 0xffff0000, v96
	v_mul_f32_e32 v0, v0, v18
	v_fmac_f32_e32 v0, v42, v22
	v_and_b32_e32 v18, 0xffff0000, v97
	v_add_f32_e32 v0, v0, v7
	v_lshlrev_b32_e32 v7, 16, v97
	v_mul_f32_e32 v1, v1, v18
	v_fmac_f32_e32 v1, v4, v7
	v_and_b32_e32 v4, 0xffff0000, v98
	v_add_f32_e32 v0, v1, v0
	v_lshlrev_b32_e32 v1, 16, v98
	v_mul_f32_e32 v2, v2, v4
	v_fmac_f32_e32 v2, v5, v1
	v_add_f32_e32 v0, v2, v0
	v_and_b32_e32 v2, 0xffff0000, v99
	v_lshlrev_b32_e32 v1, 16, v99
	v_mul_f32_e32 v2, v3, v2
	v_fmac_f32_e32 v2, v6, v1
	v_add_f32_e32 v0, v2, v0
	s_waitcnt lgkmcnt(0)
	s_nop 1
	v_add_f32_dpp v0, v0, v0 quad_perm:[1,0,3,2] row_mask:0xf bank_mask:0xf
	s_waitcnt lgkmcnt(0)
	s_nop 1
	v_add_f32_dpp v0, v0, v0 quad_perm:[2,3,0,1] row_mask:0xf bank_mask:0xf
	s_waitcnt lgkmcnt(0)
	s_nop 1
	v_add_f32_dpp v0, v0, v0 row_half_mirror row_mask:0xf bank_mask:0xf
	s_waitcnt lgkmcnt(0)
	s_nop 1
	v_add_f32_dpp v0, v0, v0 row_mirror row_mask:0xf bank_mask:0xf
	s_waitcnt lgkmcnt(0)
	v_mov_b32_e32 v1, v0
	s_nop 1
	v_permlane16_swap_b32_e32 v1, v0
	s_nop 1
	v_add_f32_e32 v0, v0, v1
	v_mov_b32_e32 v1, v0
	s_nop 1
	v_permlane32_swap_b32_e32 v1, v0
	s_nop 1
	s_and_saveexec_b64 s[70:71], vcc
	s_cbranch_execz .LBB0_523
	s_add_u32 s2, s0, s60
	s_waitcnt lgkmcnt(0)
	v_add_f32_e32 v0, v0, v1
	s_addc_u32 s3, s1, 0
	v_mov_b32_e32 v1, 0x783000
	global_store_dword v1, v0, s[2:3]
	s_branch .LBB0_523

; __device__ __forceinline__ v4u pk8(f32x4 a, f32x4 b) { v4u w; w.x = pk2(a[0], a[1]); w.y = pk2(a[2], a[3]); w.z = pk2(b[0], b[1]); w.w = pk2(b[2], b[3]); return w; }
; __device__ __forceinline__ void ld16(const unsigned short* p, f32x4 (&v)[4]) { const v4u a = ((const v4u*)p)[0], b = ((const v4u*)p)[1]; v[0] = uph4(a.x, a.y); v[1] = uph4(a.z, a.w); v[2] = uph4(b.x, b.y); v[3] = uph4(b.z, b.w); }
; __device__ __forceinline__ void st_row_norm(bf16* Y, int row, int lane, const f32x4 (&y)[4]) {
;     float ss = 0.f;
; #pragma unroll
;     for (int q = 0; q < 4; ++q) ss += (y[q][0] * y[q][0] + y[q][1] * y[q][1]) + (y[q][2] * y[q][2] + y[q][3] * y[q][3]);
;     const float rs = 1.f / sqrtf(wave_sum(ss) * (1.f / 1024.f) + EPS);
;     v4u* o = (v4u*)(Y + (size_t)row * 2048 + 16 * lane); o[0] = pk8(y[0] * rs, y[1] * rs); o[1] = pk8(y[2] * rs, y[3] * rs);
; }
; __device__ __forceinline__ void combine_phase(const unsigned short* PQ4, const float* nyq, const float* yE, const float* yO, const bf16* OP, const float* LSE, bf16* Y, int gw, int NGW, int lane) {
;     for (int t = gw; t < BATCH * 1025; t += NGW) {
;         const int b = t / 1025, k = t - b * 1025;
;         f32x4 ep[4], op[4], eq[4], oq[4], n[4];
;         const float sg = (k & 1) ? -1.f / 64.f : 1.f / 64.f;
; #pragma unroll
;         for (int q = 0; q < 4; ++q) n[q] = *(const f32x4*)(nyq + b * 1024 + 16 * lane + 4 * q) * sg;
;         if (k < 1024) { const size_t off = (size_t)k * 4096 + b * 1024 + 16 * lane;
;             ld16(PQ4 + off, ep); ld16(PQ4 + (size_t)1024 * 4096 + off, op); ld16(PQ4 + (size_t)2 * 1024 * 4096 + off, eq); ld16(PQ4 + (size_t)3 * 1024 * 4096 + off, oq);
;         } else {
; #pragma unroll
;             for (int q = 0; q < 4; ++q) { ep[q] = *(const f32x4*)(yE + b * 1024 + 16 * lane + 4 * q); oq[q] = *(const f32x4*)(yO + b * 1024 + 16 * lane + 4 * q); op[q] = (f32x4){0.f, 0.f, 0.f, 0.f}; eq[q] = op[q]; } }
;         f32x4 y[4];
; #pragma unroll
;         for (int q = 0; q < 4; ++q) y[q] = (ep[q] + op[q]) - (eq[q] + oq[q]) + n[q];
;         st_row_norm(Y, b * SEQ + k, lane, y);
.LBB0_776:
	s_bitcmp0_b32 s72, 0
	s_cselect_b64 vcc, -1, 0
	v_mov_b32_e32 v90, 0xbc800000
	v_mov_b32_e32 v91, 0x3c800000
	v_cndmask_b32_e32 v124, v90, v91, vcc
	s_waitcnt vmcnt(7)
	v_pk_add_f32 v[90:91], v[70:71], v[12:13]
	v_pk_add_f32 v[92:93], v[74:75], v[14:15]
	s_waitcnt vmcnt(0)
	v_pk_add_f32 v[94:95], v[86:87], v[28:29]
	v_pk_add_f32 v[96:97], v[88:89], v[30:31]
	v_sub_f32_e32 v101, v91, v95
	v_sub_f32_e32 v99, v93, v97
	v_sub_f32_e32 v98, v92, v96
	v_sub_f32_e32 v100, v90, v94
	v_pk_fma_f32 v[126:127], v[44:45], v[124:125], v[100:101] op_sel_hi:[1,0,1]
	v_pk_fma_f32 v[128:129], v[46:47], v[124:125], v[98:99] op_sel_hi:[1,0,1]
	v_pk_add_f32 v[100:101], v[68:69], v[10:11]
	v_pk_add_f32 v[104:105], v[84:85], v[26:27]
	v_pk_add_f32 v[98:99], v[66:67], v[8:9]
	v_pk_add_f32 v[102:103], v[82:83], v[24:25]
	v_sub_f32_e32 v107, v101, v105
	v_sub_f32_e32 v106, v100, v104
	v_pk_mul_f32 v[142:143], v[128:129], v[128:129]
	v_pk_mul_f32 v[144:145], v[126:127], v[126:127]
	v_sub_f32_e32 v109, v99, v103
	v_sub_f32_e32 v108, v98, v102
	v_pk_fma_f32 v[132:133], v[42:43], v[124:125], v[106:107] op_sel_hi:[1,0,1]
	v_pk_add_f32 v[106:107], v[62:63], v[4:5]
	v_pk_add_f32 v[110:111], v[78:79], v[20:21]
	v_pk_mov_b32 v[146:147], v[144:145], v[142:143] op_sel:[1,0]
	v_mov_b32_e32 v145, v143
	v_pk_fma_f32 v[130:131], v[40:41], v[124:125], v[108:109] op_sel_hi:[1,0,1]
	v_pk_add_f32 v[108:109], v[64:65], v[6:7]
	v_pk_add_f32 v[112:113], v[80:81], v[22:23]
	v_sub_f32_e32 v115, v107, v111
	v_sub_f32_e32 v114, v106, v110
	v_pk_add_f32 v[142:143], v[146:147], v[144:145]
	v_sub_f32_e32 v117, v109, v113
	v_sub_f32_e32 v116, v108, v112
	v_pk_fma_f32 v[136:137], v[36:37], v[124:125], v[114:115] op_sel_hi:[1,0,1]
	v_pk_add_f32 v[142:143], v[142:143], v[142:143] op_sel_hi:[0,1]
	v_pk_mul_f32 v[144:145], v[132:133], v[132:133]
	v_pk_mul_f32 v[146:147], v[130:131], v[130:131]
	v_pk_fma_f32 v[134:135], v[38:39], v[124:125], v[116:117] op_sel_hi:[1,0,1]
	v_pk_add_f32 v[114:115], v[58:59], v[0:1]
	v_pk_add_f32 v[116:117], v[60:61], v[2:3]
	v_pk_add_f32 v[118:119], v[72:73], v[16:17]
	v_pk_add_f32 v[120:121], v[76:77], v[18:19]
	v_pk_mov_b32 v[148:149], v[146:147], v[144:145] op_sel:[1,0]
	v_mov_b32_e32 v147, v145
	v_mul_f32_e32 v142, v136, v136
	v_sub_f32_e32 v139, v115, v119
	v_sub_f32_e32 v138, v114, v118
	v_sub_f32_e32 v141, v117, v121
	v_sub_f32_e32 v140, v116, v120
	v_pk_add_f32 v[144:145], v[148:149], v[146:147]
	v_pk_fma_f32 v[146:147], v[136:137], v[136:137], v[142:143] op_sel_hi:[1,1,0]
	v_mul_f32_e32 v142, v134, v134
	v_pk_fma_f32 v[140:141], v[34:35], v[124:125], v[140:141] op_sel_hi:[1,0,1]
	v_pk_fma_f32 v[138:139], v[32:33], v[124:125], v[138:139] op_sel_hi:[1,0,1]
	v_pk_add_f32 v[144:145], v[144:145], v[144:145] op_sel_hi:[0,1]
	v_pk_fma_f32 v[148:149], v[134:135], v[134:135], v[142:143] op_sel_hi:[1,1,0]
	v_mul_f32_e32 v146, v138, v138
	v_mul_f32_e32 v148, v139, v139
	v_mul_f32_e32 v142, v140, v140
	v_mul_f32_e32 v144, v141, v141
	v_pk_add_f32 v[146:147], v[146:147], v[148:149]
	v_pk_add_f32 v[142:143], v[142:143], v[144:145]
	s_mul_i32 s3, s2, 0xbff
	v_pk_add_f32 v[142:143], v[146:147], v[142:143]
	v_add_f32_e32 v123, v142, v143
	s_add_i32 s76, s1, s3
	s_ashr_i32 s77, s76, 31
	s_mulk_i32 s2, 0x1401
	s_waitcnt lgkmcnt(0)
	s_nop 1
	v_add_f32_dpp v123, v123, v123 quad_perm:[1,0,3,2] row_mask:0xf bank_mask:0xf
	s_waitcnt lgkmcnt(0)
	s_nop 1
	v_add_f32_dpp v123, v123, v123 quad_perm:[2,3,0,1] row_mask:0xf bank_mask:0xf
	s_waitcnt lgkmcnt(0)
	s_nop 1
	v_add_f32_dpp v123, v123, v123 row_half_mirror row_mask:0xf bank_mask:0xf
	s_waitcnt lgkmcnt(0)
	s_nop 1
	v_add_f32_dpp v123, v123, v123 row_mirror row_mask:0xf bank_mask:0xf
	s_waitcnt lgkmcnt(0)
	v_mov_b32_e32 v125, v123
	s_nop 1
	v_permlane16_swap_b32_e32 v125, v123
	s_nop 1
	v_add_f32_e32 v123, v123, v125
	s_waitcnt lgkmcnt(0)
	v_mov_b32_e32 v125, v123
	s_nop 1
	v_permlane32_swap_b32_e32 v125, v123
	s_nop 1
	v_add_f32_e32 v123, v123, v125
	v_fmamk_f32 v123, v123, 0x3a800000, v224
	v_pk_mul_f32 v[46:47], v[46:47], v[124:125] op_sel_hi:[1,0]
	v_pk_mul_f32 v[44:45], v[44:45], v[124:125] op_sel_hi:[1,0]
	v_pk_mul_f32 v[42:43], v[42:43], v[124:125] op_sel_hi:[1,0]
	v_pk_mul_f32 v[40:41], v[40:41], v[124:125] op_sel_hi:[1,0]
	v_mul_f32_e32 v125, 0x4f800000, v123
	v_cmp_gt_f32_e32 vcc, s41, v123
	s_nop 1
	v_cndmask_b32_e32 v123, v123, v125, vcc
	v_sqrt_f32_e32 v125, v123
	s_nop 0
	v_add_u32_e32 v142, -1, v125
	v_fma_f32 v143, -v142, v125, v123
	v_cmp_ge_f32_e64 s[4:5], 0, v143
	v_add_u32_e32 v143, 1, v125
	v_pk_mul_f32 v[38:39], v[38:39], v[124:125] op_sel_hi:[1,0]
	v_pk_mul_f32 v[36:37], v[36:37], v[124:125] op_sel_hi:[1,0]
	v_pk_mul_f32 v[34:35], v[34:35], v[124:125] op_sel_hi:[1,0]
	v_cndmask_b32_e64 v142, v125, v142, s[4:5]
	v_fma_f32 v125, -v143, v125, v123
	v_cmp_lt_f32_e64 s[4:5], 0, v125
	s_nop 1
	v_cndmask_b32_e64 v125, v142, v143, s[4:5]
	v_mul_f32_e32 v142, 0x37800000, v125
	v_cndmask_b32_e32 v125, v125, v142, vcc
	v_cmp_class_f32_e32 vcc, v123, v225
	s_nop 1
	v_cndmask_b32_e32 v123, v125, v123, vcc
	v_div_scale_f32 v125, s[4:5], v123, v123, 1.0
	v_rcp_f32_e32 v142, v125
	v_pk_mul_f32 v[32:33], v[32:33], v[124:125] op_sel_hi:[1,0]
	s_lshl_b64 s[4:5], s[76:77], 12
	s_cmp_lt_i32 s72, 1
	v_fma_f32 v124, -v125, v142, 1.0
	v_fmac_f32_e32 v142, v124, v142
	v_div_scale_f32 v124, vcc, 1.0, v123, 1.0
	v_mul_f32_e32 v143, v124, v142
	v_fma_f32 v144, -v125, v143, v124
	v_fmac_f32_e32 v143, v144, v142
	v_fma_f32 v124, -v125, v143, v124
	v_div_fmas_f32 v124, v124, v142, v143
	v_div_fixup_f32 v142, v124, v123, 1.0
	v_pk_mul_f32 v[128:129], v[128:129], v[142:143] op_sel_hi:[1,0]
	v_pk_mul_f32 v[124:125], v[126:127], v[142:143] op_sel_hi:[1,0]
	v_pk_mul_f32 v[132:133], v[132:133], v[142:143] op_sel_hi:[1,0]
	v_pk_mul_f32 v[126:127], v[130:131], v[142:143] op_sel_hi:[1,0]
	v_lshl_add_u64 v[144:145], v[56:57], 0, s[4:5]
	v_cvt_pk_bf16_f32 v124, v124, v125
	v_cvt_pk_bf16_f32 v125, v128, v129
	v_cvt_pk_bf16_f32 v126, v126, v127
	v_cvt_pk_bf16_f32 v127, v132, v133
	global_store_dwordx4 v[144:145], v[124:127], off
	v_pk_mul_f32 v[128:129], v[140:141], v[142:143] op_sel_hi:[1,0]
	v_pk_mul_f32 v[130:131], v[138:139], v[142:143] op_sel_hi:[1,0]
	v_pk_mul_f32 v[126:127], v[134:135], v[142:143] op_sel_hi:[1,0]
	v_pk_mul_f32 v[124:125], v[136:137], v[142:143] op_sel_hi:[1,0]
	s_nop 0
	v_cvt_pk_bf16_f32 v124, v124, v125
	v_cvt_pk_bf16_f32 v125, v126, v127
	v_cvt_pk_bf16_f32 v126, v130, v131
	v_cvt_pk_bf16_f32 v127, v128, v129
	global_store_dwordx4 v[144:145], v[124:127], off offset:16
	s_cbranch_scc1 .LBB0_778
; __device__ __forceinline__ v4u pk8(f32x4 a, f32x4 b) { v4u w; w.x = pk2(a[0], a[1]); w.y = pk2(a[2], a[3]); w.z = pk2(b[0], b[1]); w.w = pk2(b[2], b[3]); return w; }
; __device__ __forceinline__ void ld16(const unsigned short* p, f32x4 (&v)[4]) { const v4u a = ((const v4u*)p)[0], b = ((const v4u*)p)[1]; v[0] = uph4(a.x, a.y); v[1] = uph4(a.z, a.w); v[2] = uph4(b.x, b.y); v[3] = uph4(b.z, b.w); }
; __device__ __forceinline__ void st_row_norm(bf16* Y, int row, int lane, const f32x4 (&y)[4]) {
;     float ss = 0.f;
; #pragma unroll
;     for (int q = 0; q < 4; ++q) ss += (y[q][0] * y[q][0] + y[q][1] * y[q][1]) + (y[q][2] * y[q][2] + y[q][3] * y[q][3]);
;     const float rs = 1.f / sqrtf(wave_sum(ss) * (1.f / 1024.f) + EPS);
;     v4u* o = (v4u*)(Y + (size_t)row * 2048 + 16 * lane); o[0] = pk8(y[0] * rs, y[1] * rs); o[1] = pk8(y[2] * rs, y[3] * rs);
; }
; __device__ __forceinline__ void combine_phase(const unsigned short* PQ4, const float* nyq, const float* yE, const float* yO, const bf16* OP, const float* LSE, bf16* Y, int gw, int NGW, int lane) {
;     for (int t = gw; t < BATCH * 1025; t += NGW) {
;         const int b = t / 1025, k = t - b * 1025;
;         f32x4 ep[4], op[4], eq[4], oq[4], n[4];
;         const float sg = (k & 1) ? -1.f / 64.f : 1.f / 64.f;
; #pragma unroll
;         for (int q = 0; q < 4; ++q) n[q] = *(const f32x4*)(nyq + b * 1024 + 16 * lane + 4 * q) * sg;
;         if (k < 1024) { const size_t off = (size_t)k * 4096 + b * 1024 + 16 * lane;
;             ld16(PQ4 + off, ep); ld16(PQ4 + (size_t)1024 * 4096 + off, op); ld16(PQ4 + (size_t)2 * 1024 * 4096 + off, eq); ld16(PQ4 + (size_t)3 * 1024 * 4096 + off, oq);
;         } else {
; #pragma unroll
;             for (int q = 0; q < 4; ++q) { ep[q] = *(const f32x4*)(yE + b * 1024 + 16 * lane + 4 * q); oq[q] = *(const f32x4*)(yO + b * 1024 + 16 * lane + 4 * q); op[q] = (f32x4){0.f, 0.f, 0.f, 0.f}; eq[q] = op[q]; } }
;         f32x4 y[4];
; #pragma unroll
;         for (int q = 0; q < 4; ++q) y[q] = (ep[q] + op[q]) - (eq[q] + oq[q]) + n[q];
;         st_row_norm(Y, b * SEQ + k, lane, y);
;         if (k > 0) {
; #pragma unroll
;             for (int q = 0; q < 4; ++q) y[q] = (ep[q] + op[q]) + (eq[q] + oq[q]) + n[q];
;             st_row_norm(Y, b * SEQ + SEQ - k, lane, y); }
	v_pk_add_f32 v[92:93], v[96:97], v[92:93]
	v_pk_add_f32 v[90:91], v[94:95], v[90:91]
	v_pk_add_f32 v[92:93], v[46:47], v[92:93]
	v_pk_add_f32 v[90:91], v[44:45], v[90:91]
	v_pk_add_f32 v[94:95], v[104:105], v[100:101]
	v_pk_add_f32 v[96:97], v[102:103], v[98:99]
	v_pk_add_f32 v[98:99], v[112:113], v[108:109]
	v_pk_add_f32 v[100:101], v[110:111], v[106:107]
	v_pk_mul_f32 v[106:107], v[92:93], v[92:93]
	v_pk_mul_f32 v[108:109], v[90:91], v[90:91]
	v_pk_add_f32 v[94:95], v[42:43], v[94:95]
	v_pk_mov_b32 v[110:111], v[108:109], v[106:107] op_sel:[1,0]
	v_mov_b32_e32 v109, v107
	v_pk_add_f32 v[96:97], v[40:41], v[96:97]
	v_pk_add_f32 v[106:107], v[110:111], v[108:109]
	v_pk_add_f32 v[100:101], v[36:37], v[100:101]
	v_pk_add_f32 v[106:107], v[106:107], v[106:107] op_sel_hi:[0,1]
	v_pk_mul_f32 v[108:109], v[94:95], v[94:95]
	v_pk_mul_f32 v[110:111], v[96:97], v[96:97]
	v_pk_add_f32 v[98:99], v[38:39], v[98:99]
	v_pk_mov_b32 v[112:113], v[110:111], v[108:109] op_sel:[1,0]
	v_mov_b32_e32 v111, v109
	v_mul_f32_e32 v106, v100, v100
	v_pk_add_f32 v[102:103], v[120:121], v[116:117]
	v_pk_add_f32 v[104:105], v[118:119], v[114:115]
	v_pk_add_f32 v[108:109], v[112:113], v[110:111]
	v_pk_fma_f32 v[110:111], v[100:101], v[100:101], v[106:107] op_sel_hi:[1,1,0]
	v_mul_f32_e32 v106, v98, v98
	v_pk_add_f32 v[102:103], v[34:35], v[102:103]
	v_pk_add_f32 v[104:105], v[32:33], v[104:105]
	v_pk_add_f32 v[108:109], v[108:109], v[108:109] op_sel_hi:[0,1]
	v_pk_fma_f32 v[112:113], v[98:99], v[98:99], v[106:107] op_sel_hi:[1,1,0]
	v_mul_f32_e32 v110, v104, v104
	v_mul_f32_e32 v112, v105, v105
	v_mul_f32_e32 v106, v102, v102
	v_mul_f32_e32 v108, v103, v103
	v_pk_add_f32 v[110:111], v[110:111], v[112:113]
	v_pk_add_f32 v[106:107], v[106:107], v[108:109]
	s_add_i32 s3, s0, s2
	v_pk_add_f32 v[106:107], v[110:111], v[106:107]
	s_nop 0
	v_add_f32_e32 v106, v106, v107
	s_nop 1
	v_add_f32_dpp v106, v106, v106 quad_perm:[1,0,3,2] row_mask:0xf bank_mask:0xf
	s_nop 1
	v_add_f32_dpp v106, v106, v106 quad_perm:[2,3,0,1] row_mask:0xf bank_mask:0xf
	s_nop 1
	v_add_f32_dpp v106, v106, v106 row_half_mirror row_mask:0xf bank_mask:0xf
	s_nop 1
	v_add_f32_dpp v106, v106, v106 row_mirror row_mask:0xf bank_mask:0xf
	v_mov_b32_e32 v107, v106
	s_nop 1
	v_permlane16_swap_b32_e32 v107, v106
	s_nop 1
	v_add_f32_e32 v106, v106, v107
	v_mov_b32_e32 v107, v106
	s_nop 1
	v_permlane32_swap_b32_e32 v107, v106
	s_nop 1
	v_add_f32_e32 v106, v106, v107
	v_fmamk_f32 v106, v106, 0x3a800000, v224
	v_mul_f32_e32 v107, 0x4f800000, v106
	v_cmp_gt_f32_e32 vcc, s41, v106
	s_nop 1
	v_cndmask_b32_e32 v106, v106, v107, vcc
	v_sqrt_f32_e32 v107, v106
	s_nop 0
	v_add_u32_e32 v108, -1, v107
	v_fma_f32 v109, -v108, v107, v106
	v_cmp_ge_f32_e64 s[4:5], 0, v109
	v_add_u32_e32 v109, 1, v107
	s_nop 0
	v_cndmask_b32_e64 v108, v107, v108, s[4:5]
	v_fma_f32 v107, -v109, v107, v106
	v_cmp_lt_f32_e64 s[4:5], 0, v107
	s_nop 1
	v_cndmask_b32_e64 v107, v108, v109, s[4:5]
	v_mul_f32_e32 v108, 0x37800000, v107
	v_cndmask_b32_e32 v107, v107, v108, vcc
	v_cmp_class_f32_e32 vcc, v106, v225
	s_nop 1
	v_cndmask_b32_e32 v106, v107, v106, vcc
	v_div_scale_f32 v107, s[4:5], v106, v106, 1.0
	v_rcp_f32_e32 v108, v107
	s_add_i32 s4, s3, 0x800
	s_ashr_i32 s5, s4, 31
	s_lshl_b64 s[4:5], s[4:5], 12
	v_fma_f32 v109, -v107, v108, 1.0
	v_fmac_f32_e32 v108, v109, v108
	v_div_scale_f32 v109, vcc, 1.0, v106, 1.0
	v_mul_f32_e32 v110, v109, v108
	v_fma_f32 v111, -v107, v110, v109
	v_fmac_f32_e32 v110, v111, v108
	v_fma_f32 v107, -v107, v110, v109
	v_div_fmas_f32 v107, v107, v108, v110
	v_div_fixup_f32 v106, v107, v106, 1.0
	v_pk_mul_f32 v[92:93], v[92:93], v[106:107] op_sel_hi:[1,0]
	v_pk_mul_f32 v[90:91], v[90:91], v[106:107] op_sel_hi:[1,0]
	v_pk_mul_f32 v[94:95], v[94:95], v[106:107] op_sel_hi:[1,0]
	v_pk_mul_f32 v[96:97], v[96:97], v[106:107] op_sel_hi:[1,0]
	v_lshl_add_u64 v[108:109], v[56:57], 0, s[4:5]
	v_cvt_pk_bf16_f32 v90, v90, v91
	v_cvt_pk_bf16_f32 v91, v92, v93
	v_cvt_pk_bf16_f32 v92, v96, v97
	v_cvt_pk_bf16_f32 v93, v94, v95
	global_store_dwordx4 v[108:109], v[90:93], off
	v_pk_mul_f32 v[94:95], v[102:103], v[106:107] op_sel_hi:[1,0]
	v_pk_mul_f32 v[96:97], v[104:105], v[106:107] op_sel_hi:[1,0]
	v_pk_mul_f32 v[92:93], v[98:99], v[106:107] op_sel_hi:[1,0]
	v_pk_mul_f32 v[90:91], v[100:101], v[106:107] op_sel_hi:[1,0]
	s_nop 0
	v_cvt_pk_bf16_f32 v90, v90, v91
	v_cvt_pk_bf16_f32 v91, v92, v93
	v_cvt_pk_bf16_f32 v92, v96, v97
	v_cvt_pk_bf16_f32 v93, v94, v95
	global_store_dwordx4 v[108:109], v[90:93], off offset:16

; __device__ __forceinline__ v4u pk8(f32x4 a, f32x4 b) { v4u w; w.x = pk2(a[0], a[1]); w.y = pk2(a[2], a[3]); w.z = pk2(b[0], b[1]); w.w = pk2(b[2], b[3]); return w; }
; __device__ __forceinline__ void st_row_norm(bf16* Y, int row, int lane, const f32x4 (&y)[4]) {
;     float ss = 0.f;
; #pragma unroll
;     for (int q = 0; q < 4; ++q) ss += (y[q][0] * y[q][0] + y[q][1] * y[q][1]) + (y[q][2] * y[q][2] + y[q][3] * y[q][3]);
;     const float rs = 1.f / sqrtf(wave_sum(ss) * (1.f / 1024.f) + EPS);
;     v4u* o = (v4u*)(Y + (size_t)row * 2048 + 16 * lane); o[0] = pk8(y[0] * rs, y[1] * rs); o[1] = pk8(y[2] * rs, y[3] * rs);
; }
; __device__ __forceinline__ void combine_phase(const unsigned short* PQ4, const float* nyq, const float* yE, const float* yO, const bf16* OP, const float* LSE, bf16* Y, int gw, int NGW, int lane) {
;     for (int t = gw; t < BATCH * 1025; t += NGW) {
;         const int b = t / 1025, k = t - b * 1025;
;         f32x4 ep[4], op[4], eq[4], oq[4], n[4];
;         const float sg = (k & 1) ? -1.f / 64.f : 1.f / 64.f;
; #pragma unroll
;         for (int q = 0; q < 4; ++q) n[q] = *(const f32x4*)(nyq + b * 1024 + 16 * lane + 4 * q) * sg;
;         if (k < 1024) { const size_t off = (size_t)k * 4096 + b * 1024 + 16 * lane;
;             ld16(PQ4 + off, ep); ld16(PQ4 + (size_t)1024 * 4096 + off, op); ld16(PQ4 + (size_t)2 * 1024 * 4096 + off, eq); ld16(PQ4 + (size_t)3 * 1024 * 4096 + off, oq);
;         } else {
; #pragma unroll
;             for (int q = 0; q < 4; ++q) { ep[q] = *(const f32x4*)(yE + b * 1024 + 16 * lane + 4 * q); oq[q] = *(const f32x4*)(yO + b * 1024 + 16 * lane + 4 * q); op[q] = (f32x4){0.f, 0.f, 0.f, 0.f}; eq[q] = op[q]; } }
;         f32x4 y[4];
; #pragma unroll
;         for (int q = 0; q < 4; ++q) y[q] = (ep[q] + op[q]) - (eq[q] + oq[q]) + n[q];
;         st_row_norm(Y, b * SEQ + k, lane, y);
;         if (k > 0) {
; #pragma unroll
;             for (int q = 0; q < 4; ++q) y[q] = (ep[q] + op[q]) + (eq[q] + oq[q]) + n[q];
;             st_row_norm(Y, b * SEQ + SEQ - k, lane, y); }
;         if (k < 1024) {
; #pragma unroll
;             for (int q = 0; q < 4; ++q) y[q] = (ep[q] - op[q]) - (oq[q] - eq[q]) + n[q];
;             st_row_norm(Y, b * SEQ + SEQ / 2 - k, lane, y); }
;         if (k > 0 && k < 1024) {
.LBB0_780:
	v_sub_f32_e32 v17, v91, v31
	v_sub_f32_e32 v16, v90, v30
	v_sub_f32_e32 v19, v71, v75
	v_sub_f32_e32 v18, v70, v74
	v_pk_add_f32 v[18:19], v[44:45], v[18:19]
	v_pk_add_f32 v[16:17], v[46:47], v[16:17]
	v_pk_mul_f32 v[72:73], v[18:19], v[18:19]
	v_pk_mul_f32 v[68:69], v[16:17], v[16:17]
	v_sub_f32_e32 v23, v29, v27
	v_sub_f32_e32 v22, v28, v26
	v_sub_f32_e32 v59, v13, v25
	v_sub_f32_e32 v58, v12, v24
	v_pk_mov_b32 v[76:77], v[72:73], v[68:69] op_sel:[1,0]
	v_mov_b32_e32 v73, v69
	v_pk_add_f32 v[58:59], v[40:41], v[58:59]
	v_pk_add_f32 v[22:23], v[42:43], v[22:23]
	v_sub_f32_e32 v61, v15, v21
	v_sub_f32_e32 v60, v14, v20
	v_pk_add_f32 v[68:69], v[76:77], v[72:73]
	v_sub_f32_e32 v63, v7, v9
	v_sub_f32_e32 v62, v6, v8
	v_pk_add_f32 v[60:61], v[36:37], v[60:61]
	v_pk_add_f32 v[68:69], v[68:69], v[68:69] op_sel_hi:[0,1]
	v_pk_mul_f32 v[72:73], v[22:23], v[22:23]
	v_pk_mul_f32 v[76:77], v[58:59], v[58:59]
	v_pk_add_f32 v[62:63], v[38:39], v[62:63]
	v_pk_mov_b32 v[78:79], v[76:77], v[72:73] op_sel:[1,0]
	v_mov_b32_e32 v77, v73
	v_mul_f32_e32 v68, v60, v60
	v_sub_f32_e32 v65, v5, v11
	v_sub_f32_e32 v64, v4, v10
	v_sub_f32_e32 v67, v3, v1
	v_sub_f32_e32 v66, v2, v0
	v_pk_add_f32 v[72:73], v[78:79], v[76:77]
	v_pk_fma_f32 v[76:77], v[60:61], v[60:61], v[68:69] op_sel_hi:[1,1,0]
	v_mul_f32_e32 v68, v62, v62
	v_pk_add_f32 v[66:67], v[34:35], v[66:67]
	v_pk_add_f32 v[64:65], v[32:33], v[64:65]
	v_pk_add_f32 v[72:73], v[72:73], v[72:73] op_sel_hi:[0,1]
	v_pk_fma_f32 v[78:79], v[62:63], v[62:63], v[68:69] op_sel_hi:[1,1,0]
	v_mul_f32_e32 v76, v64, v64
	v_mul_f32_e32 v78, v65, v65
	v_mul_f32_e32 v68, v66, v66
	v_mul_f32_e32 v72, v67, v67
	v_pk_add_f32 v[76:77], v[76:77], v[78:79]
	v_pk_add_f32 v[68:69], v[68:69], v[72:73]
	s_add_i32 s2, s0, s2
	v_pk_add_f32 v[68:69], v[76:77], v[68:69]
	s_ashr_i32 s3, s2, 31
	v_add_f32_e32 v68, v68, v69
	s_lshl_b64 s[2:3], s[2:3], 12
	s_waitcnt lgkmcnt(0)
	s_nop 1
	v_add_f32_dpp v68, v68, v68 quad_perm:[1,0,3,2] row_mask:0xf bank_mask:0xf
	s_waitcnt lgkmcnt(0)
	s_nop 1
	v_add_f32_dpp v68, v68, v68 quad_perm:[2,3,0,1] row_mask:0xf bank_mask:0xf
	s_waitcnt lgkmcnt(0)
	s_nop 1
	v_add_f32_dpp v68, v68, v68 row_half_mirror row_mask:0xf bank_mask:0xf
	s_waitcnt lgkmcnt(0)
	s_nop 1
	v_add_f32_dpp v68, v68, v68 row_mirror row_mask:0xf bank_mask:0xf
	s_waitcnt lgkmcnt(0)
	v_mov_b32_e32 v69, v68
	s_nop 1
	v_permlane16_swap_b32_e32 v69, v68
	s_nop 1
	v_add_f32_e32 v68, v68, v69
	s_waitcnt lgkmcnt(0)
	v_mov_b32_e32 v69, v68
	s_nop 1
	v_permlane32_swap_b32_e32 v69, v68
	s_nop 1
	v_add_f32_e32 v68, v68, v69
	v_fmamk_f32 v68, v68, 0x3a800000, v224
	v_mul_f32_e32 v69, 0x4f800000, v68
	v_cmp_gt_f32_e32 vcc, s41, v68
	s_nop 1
	v_cndmask_b32_e32 v68, v68, v69, vcc
	v_sqrt_f32_e32 v69, v68
	s_nop 0
	v_add_u32_e32 v72, -1, v69
	v_fma_f32 v73, -v72, v69, v68
	v_cmp_ge_f32_e64 s[4:5], 0, v73
	v_add_u32_e32 v73, 1, v69
	s_nop 0
	v_cndmask_b32_e64 v72, v69, v72, s[4:5]
	v_fma_f32 v69, -v73, v69, v68
	v_cmp_lt_f32_e64 s[4:5], 0, v69
	s_nop 1
	v_cndmask_b32_e64 v69, v72, v73, s[4:5]
	v_mul_f32_e32 v72, 0x37800000, v69
	v_cndmask_b32_e32 v69, v69, v72, vcc
	v_cmp_class_f32_e32 vcc, v68, v225
	s_nop 1
	v_cndmask_b32_e32 v68, v69, v68, vcc
	v_div_scale_f32 v69, s[4:5], v68, v68, 1.0
	v_rcp_f32_e32 v72, v69
	s_nop 0
	v_fma_f32 v73, -v69, v72, 1.0
	v_fmac_f32_e32 v72, v73, v72
	v_div_scale_f32 v73, vcc, 1.0, v68, 1.0
	v_mul_f32_e32 v76, v73, v72
	v_fma_f32 v77, -v69, v76, v73
	v_fmac_f32_e32 v76, v77, v72
	v_fma_f32 v69, -v69, v76, v73
	v_div_fmas_f32 v69, v69, v72, v76
	v_div_fixup_f32 v68, v69, v68, 1.0
	v_pk_mul_f32 v[76:77], v[16:17], v[68:69] op_sel_hi:[1,0]
	v_pk_mul_f32 v[16:17], v[18:19], v[68:69] op_sel_hi:[1,0]
	v_pk_mul_f32 v[22:23], v[22:23], v[68:69] op_sel_hi:[1,0]
	v_pk_mul_f32 v[18:19], v[58:59], v[68:69] op_sel_hi:[1,0]
	v_lshl_add_u64 v[72:73], v[56:57], 0, s[2:3]
	v_cvt_pk_bf16_f32 v16, v16, v17
	v_cvt_pk_bf16_f32 v17, v76, v77
	v_cvt_pk_bf16_f32 v18, v18, v19
	v_cvt_pk_bf16_f32 v19, v22, v23
	global_store_dwordx4 v[72:73], v[16:19], off
	v_pk_mul_f32 v[22:23], v[66:67], v[68:69] op_sel_hi:[1,0]
	v_pk_mul_f32 v[58:59], v[64:65], v[68:69] op_sel_hi:[1,0]
	v_pk_mul_f32 v[18:19], v[62:63], v[68:69] op_sel_hi:[1,0]
	v_pk_mul_f32 v[16:17], v[60:61], v[68:69] op_sel_hi:[1,0]
	s_nop 0
	v_cvt_pk_bf16_f32 v16, v16, v17
	v_cvt_pk_bf16_f32 v17, v18, v19
	v_cvt_pk_bf16_f32 v18, v58, v59
	v_cvt_pk_bf16_f32 v19, v22, v23
	global_store_dwordx4 v[72:73], v[16:19], off offset:16
	s_add_i32 s2, s72, -1
	s_cmpk_gt_u32 s2, 0x3fe
	s_cbranch_scc1 .LBB0_771
